# SSD state update: decay scalar read at the epilogue start, first 8 transposed reads issued before the state scaling
# baseline (speedup 1.0000x reference)
; __device__ __forceinline__ float ex2(float x) { return __builtin_amdgcn_exp2f(x); }
; __device__ __forceinline__ float silu_f(float x) { return x * sigm(x); }
; #define GAS __attribute__((address_space(1)))
; #define LAS __attribute__((address_space(3)))
; __device__ __forceinline__ void ssd_stream(const Frame& F, const Args& A, int sidx) {
;     ...
;         {
;             GAS unsigned char* yb = YGg + (size_t)t0 * 4096;
;             float ssq = 0.f;
; #pragma unroll
;             for (int q4 = 0; q4 < 4; ++q4) {
;                 const int p0 = 32 * pt + 8 * q4 + 4 * hh;
;                 const v2u xw = *(LAS v2u*)(XT + lcol * XS_ + p0 * 2);
;                 const float y0 = (Y[4 * q4 + 0] + Dsk * bflo(xw.x)) * silu_f(bflo(zw[q4].x)), y1 = (Y[4 * q4 + 1] + Dsk * bfhi(xw.x)) * silu_f(bfhi(zw[q4].x));
;     ...
;             const float eL = ex2(arr[127]);
.LBB0_1312:
	v_mov_b32_e32 v252, s78
	ds_read_b32 v253, v252 offset:508
	ds_read_b64 v[36:37], v226
	ds_read_b64 v[38:39], v226 offset:16
	ds_read_b64 v[40:41], v226 offset:32
	ds_read_b64 v[42:43], v226 offset:48
	v_lshl_add_u64 v[34:35], v[154:155], 0, s[64:65]
	v_and_b32_e32 v46, 32, v202
	v_lshrrev_b32_e32 v46, 2, v46
	v_add_co_u32_e32 v34, vcc, v34, v46
	v_mov_b32_e32 v44, v141
	v_addc_co_u32_e32 v35, vcc, 0, v35, vcc
	v_mov_b32_e32 v45, v141
	s_andn2_b64 vcc, exec, s[60:61]
	s_cbranch_vccnz .LZW_last
	s_waitcnt vmcnt(12)
	s_branch .LZW_go

; __device__ __forceinline__ float ex2(float x) { return __builtin_amdgcn_exp2f(x); }
; #define LAS __attribute__((address_space(3)))
; __device__ __forceinline__ s16x4 trr(LAS unsigned char* p) { return __builtin_bit_cast(s16x4, __builtin_amdgcn_ds_read_tr16_b64_v4i16((LAS v4i16_t*)p)); }
; __device__ __forceinline__ bf16x8 cat8(s16x4 lo, s16x4 hi) { return (bf16x8){lo[0], lo[1], lo[2], lo[3], hi[0], hi[1], hi[2], hi[3]}; }
; #define MFMA32(a, b, c) __builtin_amdgcn_mfma_f32_32x32x16_bf16((a), (b), (c), 0, 0, 0)
; __device__ __forceinline__ void ssd_stream(const Frame& F, const Args& A, int sidx) {
;     ...
;         {
;             const float eL = ex2(arr[127]);
; #pragma unroll
;             for (int i = 0; i < 16; ++i) st[i] *= eL;
; #pragma unroll
;             for (int kg = 0; kg < 2; ++kg) {
;                 s16x4 alo[4], ahi[4], blo[4], bhi[4];
; #pragma unroll
;                 for (int k4 = 0; k4 < 4; ++k4) { const int ks = 4 * kg + k4;
;                     LAS unsigned char* ba = BT + (16 * ks + 8 * hh + qq) * BS_ + (32 * nt + 16 * cb16 + 4 * pp) * 2;
;                     LAS unsigned char* xa = XST + (16 * ks + 8 * hh + qq) * XS_ + (32 * pt + 16 * cb16 + 4 * pp) * 2;
;                     alo[k4] = trr(ba); ahi[k4] = trr(ba + 4 * BS_); blo[k4] = trr(xa); bhi[k4] = trr(xa + 4 * XS_); }
;                 __builtin_amdgcn_sched_barrier(0);
; #pragma unroll
;                 for (int k4 = 0; k4 < 4; ++k4) st = MFMA32(cat8(alo[k4], ahi[k4]), cat8(blo[k4], bhi[k4]), st);
;             }
;         }
;         if (ck < 63) SSD_SCAN((LAS float*)(F.lds + L_ARR + ((ck + 1) & 1) * 1536));
.LBB0_1314:
	s_or_b64 exec, exec, s[26:27]
	s_waitcnt lgkmcnt(0)
	v_add_u32_e32 v19, v209, v211
	v_exp_f32_e32 v252, v253
	ds_read_b64_tr_b16 v[20:21], v19 offset:36864
	ds_read_b64_tr_b16 v[22:23], v19 offset:37952
	ds_read_b64_tr_b16 v[24:25], v227 offset:18432
	ds_read_b64_tr_b16 v[26:27], v227 offset:19008
	ds_read_b64_tr_b16 v[28:29], v19 offset:41216
	ds_read_b64_tr_b16 v[30:31], v19 offset:42304
	ds_read_b64_tr_b16 v[32:33], v227 offset:20736
	ds_read_b64_tr_b16 v[34:35], v227 offset:21312
	v_pk_mul_f32 v[16:17], v[16:17], v[252:253] op_sel_hi:[1,0]
	v_pk_mul_f32 v[14:15], v[14:15], v[252:253] op_sel_hi:[1,0]
	v_pk_mul_f32 v[12:13], v[12:13], v[252:253] op_sel_hi:[1,0]
	v_pk_mul_f32 v[10:11], v[10:11], v[252:253] op_sel_hi:[1,0]
	v_pk_mul_f32 v[8:9], v[8:9], v[252:253] op_sel_hi:[1,0]
	v_pk_mul_f32 v[6:7], v[6:7], v[252:253] op_sel_hi:[1,0]
	v_pk_mul_f32 v[4:5], v[4:5], v[252:253] op_sel_hi:[1,0]
	v_pk_mul_f32 v[2:3], v[2:3], v[252:253] op_sel_hi:[1,0]
	ds_read_b64_tr_b16 v[36:37], v19 offset:45568
	ds_read_b64_tr_b16 v[38:39], v19 offset:46656
	ds_read_b64_tr_b16 v[40:41], v227 offset:23040
	ds_read_b64_tr_b16 v[42:43], v227 offset:23616
	ds_read_b64_tr_b16 v[44:45], v19 offset:49920
	ds_read_b64_tr_b16 v[46:47], v19 offset:51008
	ds_read_b64_tr_b16 v[98:99], v227 offset:25344
	ds_read_b64_tr_b16 v[100:101], v227 offset:25920
	s_waitcnt lgkmcnt(12)
	v_mfma_f32_32x32x16_bf16 v[2:17], v[20:23], v[24:27], v[2:17]
	s_waitcnt lgkmcnt(8)
	v_mfma_f32_32x32x16_bf16 v[2:17], v[28:31], v[32:35], v[2:17]
	s_waitcnt lgkmcnt(4)
	v_mfma_f32_32x32x16_bf16 v[2:17], v[36:39], v[40:43], v[2:17]
	s_waitcnt lgkmcnt(0)
	v_mfma_f32_32x32x16_bf16 v[2:17], v[44:47], v[98:101], v[2:17]
	ds_read_b64_tr_b16 v[20:21], v19 offset:54272
	ds_read_b64_tr_b16 v[22:23], v19 offset:55360
	ds_read_b64_tr_b16 v[24:25], v227 offset:27648
	ds_read_b64_tr_b16 v[26:27], v227 offset:28224
	ds_read_b64_tr_b16 v[28:29], v19 offset:58624
	ds_read_b64_tr_b16 v[30:31], v19 offset:59712
	ds_read_b64_tr_b16 v[32:33], v227 offset:29952
	ds_read_b64_tr_b16 v[34:35], v227 offset:30528
	ds_read_b64_tr_b16 v[36:37], v19 offset:62976
	ds_read_b64_tr_b16 v[38:39], v19 offset:64064
	ds_read_b64_tr_b16 v[40:41], v227 offset:32256
	ds_read_b64_tr_b16 v[42:43], v227 offset:32832
	ds_read_b64_tr_b16 v[44:45], v228 offset:62976
	ds_read_b64_tr_b16 v[46:47], v228 offset:64064
	ds_read_b64_tr_b16 v[98:99], v227 offset:34560
	ds_read_b64_tr_b16 v[100:101], v227 offset:35136
	s_waitcnt lgkmcnt(12)
	v_mfma_f32_32x32x16_bf16 v[2:17], v[20:23], v[24:27], v[2:17]
	s_and_b64 s[26:27], s[96:97], s[60:61]
	s_andn2_b64 vcc, exec, s[26:27]
	s_waitcnt lgkmcnt(8)
	v_mfma_f32_32x32x16_bf16 v[2:17], v[28:31], v[32:35], v[2:17]
	s_waitcnt lgkmcnt(4)
	v_mfma_f32_32x32x16_bf16 v[2:17], v[36:39], v[40:43], v[2:17]
	s_waitcnt lgkmcnt(0)
	v_mfma_f32_32x32x16_bf16 v[2:17], v[44:47], v[98:101], v[2:17]
	s_cbranch_vccnz .LBB0_1292
	s_waitcnt vmcnt(14)
	v_pk_mul_f32 v[20:21], v[148:149], v[146:147]
	v_add_u32_e32 v22, -2, v202
	v_add_f32_e32 v19, v21, v20
	v_add_u32_e32 v20, -1, v202
	v_cmp_lt_i32_e32 vcc, v20, v18
	s_andn2_b32 s26, 1, s5
	s_mulk_i32 s26, 0x600
	v_cndmask_b32_e32 v20, v20, v202, vcc
	v_lshlrev_b32_e32 v20, 2, v20
	ds_bpermute_b32 v20, v20, v19
	v_cmp_lt_i32_e32 vcc, v22, v18
	s_waitcnt lgkmcnt(0)
	v_add_f32_e32 v20, v19, v20
	v_cndmask_b32_e64 v19, v20, v19, s[14:15]
	v_cndmask_b32_e32 v20, v22, v202, vcc
	v_lshlrev_b32_e32 v20, 2, v20
	ds_bpermute_b32 v20, v20, v19
	v_add_u32_e32 v22, -4, v202
	v_cmp_lt_i32_e32 vcc, v22, v18
	s_waitcnt lgkmcnt(0)
	v_add_f32_e32 v20, v19, v20
	v_cndmask_b32_e64 v19, v20, v19, s[16:17]
	v_cndmask_b32_e32 v20, v22, v202, vcc
	v_lshlrev_b32_e32 v20, 2, v20
	ds_bpermute_b32 v20, v20, v19
	v_add_u32_e32 v22, -8, v202
	v_cmp_lt_i32_e32 vcc, v22, v18
	s_waitcnt lgkmcnt(0)
	v_add_f32_e32 v20, v19, v20
	v_cndmask_b32_e64 v19, v20, v19, s[18:19]
	v_cndmask_b32_e32 v20, v22, v202, vcc
	v_lshlrev_b32_e32 v20, 2, v20
	ds_bpermute_b32 v20, v20, v19
	v_add_u32_e32 v22, -16, v202
	v_cmp_lt_i32_e32 vcc, v22, v18
	s_waitcnt lgkmcnt(0)
	v_add_f32_e32 v20, v19, v20
	v_cndmask_b32_e64 v19, v20, v19, s[20:21]
	v_cndmask_b32_e32 v20, v22, v202, vcc
	v_lshlrev_b32_e32 v20, 2, v20
	ds_bpermute_b32 v20, v20, v19
	v_subrev_u32_e32 v22, 32, v202
	v_cmp_lt_i32_e32 vcc, v22, v18
	v_add_lshl_u32 v18, v18, v203, 2
	s_waitcnt lgkmcnt(0)
	v_add_f32_e32 v20, v19, v20
	v_cndmask_b32_e64 v19, v20, v19, s[22:23]
	v_cndmask_b32_e32 v20, v22, v202, vcc
	v_lshlrev_b32_e32 v20, 2, v20
	ds_bpermute_b32 v20, v20, v19
	s_waitcnt lgkmcnt(0)
	v_add_f32_e32 v20, v19, v20
	v_cndmask_b32_e64 v19, v20, v19, s[24:25]
	ds_bpermute_b32 v20, v18, v19
	v_sub_f32_e32 v18, v19, v21
	s_waitcnt lgkmcnt(0)
	v_sub_f32_e32 v21, v20, v18
	v_sub_f32_e32 v22, v20, v19
	v_exp_f32_e32 v20, v21
	v_exp_f32_e32 v21, v22
	v_add_u32_e32 v22, s26, v220
	ds_write2st64_b64 v22, v[18:19], v[146:147] offset1:1
	v_pk_mul_f32 v[18:19], v[146:147], v[20:21]
	ds_write_b64 v22, v[18:19] offset:1024
	s_branch .LBB0_1292
